# pool_phase window prologue: up to 15 history-row loads issued at once under lane masks (was one round trip per row)
# speedup vs baseline: 1.0036x; 1.0010x over previous
; __device__ __forceinline__ void pool_phase(const bf16_t* __restrict__ H, bf16_t* __restrict__ AO, int gtid, int gthreads) {
;     for (int idx = gtid; idx < (M / 32) * 96; idx += gthreads) {
;         const int c = idx % 96, run = idx / 96, t0 = run * 32, tl0 = t0 & (SEQ - 1);
;         const int w = 2 << (c / 24);
;         const bf16_t* base = H + (size_t)t0 * 1024 + c * 8;
;         float S[8], v[8];
; #pragma unroll
;         for (int e = 0; e < 8; ++e) S[e] = 0.f;
;         for (int j = 1; j < w; ++j) if (tl0 - j >= 0) { unpack8(*(const u32x4*)(base - (size_t)j * 1024), v);
; #pragma unroll
;             for (int e = 0; e < 8; ++e) S[e] += v[e]; }
.LBB0_944:
	v_mul_hi_i32 v0, v138, s5
	s_waitcnt lgkmcnt(0)
	v_lshrrev_b32_e32 v1, 31, v0
	v_ashrrev_i32_e32 v0, 4, v0
	v_add_u32_e32 v0, v0, v1
	s_movk_i32 s24, 0x60
	v_mul_lo_u32 v1, v0, s24
	s_waitcnt lgkmcnt(0)
	v_sub_u32_e32 v2, v138, v1
	v_lshlrev_b32_e32 v128, 5, v0
	v_mul_lo_u16_e32 v0, 43, v2
	v_lshrrev_b16_e32 v1, 15, v0
	v_ashrrev_i16_e32 v0, 10, v0
	v_add_u16_e32 v4, v0, v1
	v_ashrrev_i32_e32 v129, 31, v128
	v_lshlrev_b32_e32 v2, 3, v2
	v_mov_b32_e32 v153, 0
	v_lshlrev_b64 v[0:1], 11, v[128:129]
	v_ashrrev_i32_e32 v3, 31, v2
	v_and_b32_e32 v129, 0x3fe0, v128
	v_lshlrev_b32_e64 v166, v4, 2
	v_cmp_gt_u16_e32 vcc, 31, v4
	v_mov_b32_e32 v152, v153
	v_mov_b32_e32 v151, v153
	v_mov_b32_e32 v150, v153
	v_mov_b32_e32 v149, v153
	v_mov_b32_e32 v148, v153
	v_mov_b32_e32 v135, v153
	v_mov_b32_e32 v134, v153
	s_and_saveexec_b64 s[24:25], vcc
	s_cbranch_execz .LBB0_950
	v_lshl_add_u64 v[4:5], v[2:3], 1, v[0:1]
	v_lshl_add_u64 v[4:5], s[38:39], 0, v[4:5]
	v_add_u32_e32 v6, 1, v129
	v_min_u32_e32 v6, v6, v166
	s_mov_b32 s27, -1
	s_mov_b32 s26, 0xffffe800
	v_lshl_add_u64 v[12:13], v[4:5], 0, s[26:27]
	s_mov_b32 s26, 0xffffd000
	v_lshl_add_u64 v[14:15], v[4:5], 0, s[26:27]
	s_mov_b32 s26, 0xffffb800
	v_lshl_add_u64 v[16:17], v[4:5], 0, s[26:27]
	s_mov_b32 s26, 0xffffa000
	v_lshl_add_u64 v[18:19], v[4:5], 0, s[26:27]
	v_mov_b32_e32 v134, 0
	v_mov_b32_e32 v135, 0
	v_mov_b32_e32 v148, 0
	v_mov_b32_e32 v149, 0
	v_mov_b32_e32 v150, 0
	v_mov_b32_e32 v151, 0
	v_mov_b32_e32 v152, 0
	v_mov_b32_e32 v153, 0
	v_mov_b32_e32 v64, 0
	v_mov_b32_e32 v65, 0
	v_mov_b32_e32 v66, 0
	v_mov_b32_e32 v67, 0
	v_mov_b32_e32 v68, 0
	v_mov_b32_e32 v69, 0
	v_mov_b32_e32 v70, 0
	v_mov_b32_e32 v71, 0
	v_mov_b32_e32 v72, 0
	v_mov_b32_e32 v73, 0
	v_mov_b32_e32 v74, 0
	v_mov_b32_e32 v75, 0
	v_mov_b32_e32 v76, 0
	v_mov_b32_e32 v77, 0
	v_mov_b32_e32 v78, 0
	v_mov_b32_e32 v79, 0
	v_mov_b32_e32 v80, 0
	v_mov_b32_e32 v81, 0
	v_mov_b32_e32 v82, 0
	v_mov_b32_e32 v83, 0
	v_mov_b32_e32 v84, 0
	v_mov_b32_e32 v85, 0
	v_mov_b32_e32 v86, 0
	v_mov_b32_e32 v87, 0
	v_mov_b32_e32 v88, 0
	v_mov_b32_e32 v89, 0
	v_mov_b32_e32 v90, 0
	v_mov_b32_e32 v91, 0
	v_mov_b32_e32 v92, 0
	v_mov_b32_e32 v93, 0
	v_mov_b32_e32 v94, 0
	v_mov_b32_e32 v95, 0
	v_mov_b32_e32 v96, 0
	v_mov_b32_e32 v97, 0
	v_mov_b32_e32 v98, 0
	v_mov_b32_e32 v99, 0
	v_mov_b32_e32 v100, 0
	v_mov_b32_e32 v101, 0
	v_mov_b32_e32 v102, 0
	v_mov_b32_e32 v103, 0
	v_mov_b32_e32 v104, 0
	v_mov_b32_e32 v105, 0
	v_mov_b32_e32 v106, 0
	v_mov_b32_e32 v107, 0
	v_mov_b32_e32 v108, 0
	v_mov_b32_e32 v109, 0
	v_mov_b32_e32 v110, 0
	v_mov_b32_e32 v111, 0
	v_mov_b32_e32 v112, 0
	v_mov_b32_e32 v113, 0
	v_mov_b32_e32 v114, 0
	v_mov_b32_e32 v115, 0
	v_mov_b32_e32 v116, 0
	v_mov_b32_e32 v117, 0
	v_mov_b32_e32 v118, 0
	v_mov_b32_e32 v119, 0
	v_mov_b32_e32 v120, 0
	v_mov_b32_e32 v121, 0
	v_mov_b32_e32 v122, 0
	v_mov_b32_e32 v123, 0
	v_cmp_lt_u32_e32 vcc, 1, v6
	s_and_saveexec_b64 s[28:29], vcc
	global_load_dwordx4 v[64:67], v[4:5], off
	s_mov_b64 exec, s[28:29]
	v_cmp_lt_u32_e32 vcc, 2, v6
	s_and_saveexec_b64 s[28:29], vcc
	global_load_dwordx4 v[68:71], v[4:5], off offset:-2048
	s_mov_b64 exec, s[28:29]
	v_cmp_lt_u32_e32 vcc, 3, v6
	s_and_saveexec_b64 s[28:29], vcc
	global_load_dwordx4 v[72:75], v[4:5], off offset:-4096
	s_mov_b64 exec, s[28:29]
	v_cmp_lt_u32_e32 vcc, 4, v6
	s_and_saveexec_b64 s[28:29], vcc
	global_load_dwordx4 v[76:79], v[12:13], off
	s_mov_b64 exec, s[28:29]
	v_cmp_lt_u32_e32 vcc, 5, v6
	s_and_saveexec_b64 s[28:29], vcc
	global_load_dwordx4 v[80:83], v[12:13], off offset:-2048
	s_mov_b64 exec, s[28:29]
	v_cmp_lt_u32_e32 vcc, 6, v6
	s_and_saveexec_b64 s[28:29], vcc
	global_load_dwordx4 v[84:87], v[12:13], off offset:-4096
	s_mov_b64 exec, s[28:29]
	v_cmp_lt_u32_e32 vcc, 7, v6
	s_and_saveexec_b64 s[28:29], vcc
	global_load_dwordx4 v[88:91], v[14:15], off
	s_mov_b64 exec, s[28:29]
	v_cmp_lt_u32_e32 vcc, 8, v6
	s_and_saveexec_b64 s[28:29], vcc
	global_load_dwordx4 v[92:95], v[14:15], off offset:-2048
	s_mov_b64 exec, s[28:29]
	v_cmp_lt_u32_e32 vcc, 9, v6
	s_and_saveexec_b64 s[28:29], vcc
	global_load_dwordx4 v[96:99], v[14:15], off offset:-4096
	s_mov_b64 exec, s[28:29]
	v_cmp_lt_u32_e32 vcc, 10, v6
	s_and_saveexec_b64 s[28:29], vcc
	global_load_dwordx4 v[100:103], v[16:17], off
	s_mov_b64 exec, s[28:29]
	v_cmp_lt_u32_e32 vcc, 11, v6
	s_and_saveexec_b64 s[28:29], vcc
	global_load_dwordx4 v[104:107], v[16:17], off offset:-2048
	s_mov_b64 exec, s[28:29]
	v_cmp_lt_u32_e32 vcc, 12, v6
	s_and_saveexec_b64 s[28:29], vcc
	global_load_dwordx4 v[108:111], v[16:17], off offset:-4096
	s_mov_b64 exec, s[28:29]
	v_cmp_lt_u32_e32 vcc, 13, v6
	s_and_saveexec_b64 s[28:29], vcc
	global_load_dwordx4 v[112:115], v[18:19], off
	s_mov_b64 exec, s[28:29]
	v_cmp_lt_u32_e32 vcc, 14, v6
	s_and_saveexec_b64 s[28:29], vcc
	global_load_dwordx4 v[116:119], v[18:19], off offset:-2048
	s_mov_b64 exec, s[28:29]
	v_cmp_lt_u32_e32 vcc, 15, v6
	s_and_saveexec_b64 s[28:29], vcc
	global_load_dwordx4 v[120:123], v[18:19], off offset:-4096
	s_mov_b64 exec, s[28:29]
	s_waitcnt vmcnt(0)
; __device__ __forceinline__ void unpack8(const u32x4 w, float* f) {
;     f[0] = __uint_as_float(w.x << 16); f[1] = __uint_as_float(w.x & 0xffff0000u); f[2] = __uint_as_float(w.y << 16); f[3] = __uint_as_float(w.y & 0xffff0000u);
;     f[4] = __uint_as_float(w.z << 16); f[5] = __uint_as_float(w.z & 0xffff0000u); f[6] = __uint_as_float(w.w << 16); f[7] = __uint_as_float(w.w & 0xffff0000u);
; __device__ __forceinline__ void pool_phase(const bf16_t* __restrict__ H, bf16_t* __restrict__ AO, int gtid, int gthreads) {
;     ...
;         for (int j = 1; j < w; ++j) if (tl0 - j >= 0) { unpack8(*(const u32x4*)(base - (size_t)j * 1024), v);
; #pragma unroll
;             for (int e = 0; e < 8; ++e) S[e] += v[e]; }
	v_lshlrev_b32_e32 v8, 16, v64
	v_and_b32_e32 v9, 0xffff0000, v64
	v_pk_add_f32 v[134:135], v[134:135], v[8:9]
	v_lshlrev_b32_e32 v8, 16, v65
	v_and_b32_e32 v9, 0xffff0000, v65
	v_pk_add_f32 v[148:149], v[148:149], v[8:9]
	v_lshlrev_b32_e32 v8, 16, v66
	v_and_b32_e32 v9, 0xffff0000, v66
	v_pk_add_f32 v[150:151], v[150:151], v[8:9]
	v_lshlrev_b32_e32 v8, 16, v67
	v_and_b32_e32 v9, 0xffff0000, v67
	v_pk_add_f32 v[152:153], v[152:153], v[8:9]
	v_lshlrev_b32_e32 v8, 16, v68
	v_and_b32_e32 v9, 0xffff0000, v68
	v_pk_add_f32 v[134:135], v[134:135], v[8:9]
	v_lshlrev_b32_e32 v8, 16, v69
	v_and_b32_e32 v9, 0xffff0000, v69
	v_pk_add_f32 v[148:149], v[148:149], v[8:9]
	v_lshlrev_b32_e32 v8, 16, v70
	v_and_b32_e32 v9, 0xffff0000, v70
	v_pk_add_f32 v[150:151], v[150:151], v[8:9]
	v_lshlrev_b32_e32 v8, 16, v71
	v_and_b32_e32 v9, 0xffff0000, v71
	v_pk_add_f32 v[152:153], v[152:153], v[8:9]
	v_lshlrev_b32_e32 v8, 16, v72
	v_and_b32_e32 v9, 0xffff0000, v72
	v_pk_add_f32 v[134:135], v[134:135], v[8:9]
	v_lshlrev_b32_e32 v8, 16, v73
	v_and_b32_e32 v9, 0xffff0000, v73
	v_pk_add_f32 v[148:149], v[148:149], v[8:9]
	v_lshlrev_b32_e32 v8, 16, v74
	v_and_b32_e32 v9, 0xffff0000, v74
	v_pk_add_f32 v[150:151], v[150:151], v[8:9]
	v_lshlrev_b32_e32 v8, 16, v75
	v_and_b32_e32 v9, 0xffff0000, v75
	v_pk_add_f32 v[152:153], v[152:153], v[8:9]
	v_lshlrev_b32_e32 v8, 16, v76
	v_and_b32_e32 v9, 0xffff0000, v76
	v_pk_add_f32 v[134:135], v[134:135], v[8:9]
	v_lshlrev_b32_e32 v8, 16, v77
	v_and_b32_e32 v9, 0xffff0000, v77
	v_pk_add_f32 v[148:149], v[148:149], v[8:9]
	v_lshlrev_b32_e32 v8, 16, v78
	v_and_b32_e32 v9, 0xffff0000, v78
	v_pk_add_f32 v[150:151], v[150:151], v[8:9]
	v_lshlrev_b32_e32 v8, 16, v79
	v_and_b32_e32 v9, 0xffff0000, v79
	v_pk_add_f32 v[152:153], v[152:153], v[8:9]
	v_lshlrev_b32_e32 v8, 16, v80
	v_and_b32_e32 v9, 0xffff0000, v80
	v_pk_add_f32 v[134:135], v[134:135], v[8:9]
	v_lshlrev_b32_e32 v8, 16, v81
	v_and_b32_e32 v9, 0xffff0000, v81
	v_pk_add_f32 v[148:149], v[148:149], v[8:9]
	v_lshlrev_b32_e32 v8, 16, v82
	v_and_b32_e32 v9, 0xffff0000, v82
	v_pk_add_f32 v[150:151], v[150:151], v[8:9]
	v_lshlrev_b32_e32 v8, 16, v83
	v_and_b32_e32 v9, 0xffff0000, v83
	v_pk_add_f32 v[152:153], v[152:153], v[8:9]
	v_lshlrev_b32_e32 v8, 16, v84
	v_and_b32_e32 v9, 0xffff0000, v84
	v_pk_add_f32 v[134:135], v[134:135], v[8:9]
	v_lshlrev_b32_e32 v8, 16, v85
	v_and_b32_e32 v9, 0xffff0000, v85
	v_pk_add_f32 v[148:149], v[148:149], v[8:9]
	v_lshlrev_b32_e32 v8, 16, v86
	v_and_b32_e32 v9, 0xffff0000, v86
	v_pk_add_f32 v[150:151], v[150:151], v[8:9]
	v_lshlrev_b32_e32 v8, 16, v87
	v_and_b32_e32 v9, 0xffff0000, v87
	v_pk_add_f32 v[152:153], v[152:153], v[8:9]
	v_lshlrev_b32_e32 v8, 16, v88
	v_and_b32_e32 v9, 0xffff0000, v88
	v_pk_add_f32 v[134:135], v[134:135], v[8:9]
	v_lshlrev_b32_e32 v8, 16, v89
	v_and_b32_e32 v9, 0xffff0000, v89
	v_pk_add_f32 v[148:149], v[148:149], v[8:9]
	v_lshlrev_b32_e32 v8, 16, v90
	v_and_b32_e32 v9, 0xffff0000, v90
	v_pk_add_f32 v[150:151], v[150:151], v[8:9]
	v_lshlrev_b32_e32 v8, 16, v91
	v_and_b32_e32 v9, 0xffff0000, v91
	v_pk_add_f32 v[152:153], v[152:153], v[8:9]
	v_lshlrev_b32_e32 v8, 16, v92
	v_and_b32_e32 v9, 0xffff0000, v92
	v_pk_add_f32 v[134:135], v[134:135], v[8:9]
	v_lshlrev_b32_e32 v8, 16, v93
	v_and_b32_e32 v9, 0xffff0000, v93
	v_pk_add_f32 v[148:149], v[148:149], v[8:9]
	v_lshlrev_b32_e32 v8, 16, v94
	v_and_b32_e32 v9, 0xffff0000, v94
	v_pk_add_f32 v[150:151], v[150:151], v[8:9]
	v_lshlrev_b32_e32 v8, 16, v95
	v_and_b32_e32 v9, 0xffff0000, v95
	v_pk_add_f32 v[152:153], v[152:153], v[8:9]
	v_lshlrev_b32_e32 v8, 16, v96
	v_and_b32_e32 v9, 0xffff0000, v96
	v_pk_add_f32 v[134:135], v[134:135], v[8:9]
	v_lshlrev_b32_e32 v8, 16, v97
	v_and_b32_e32 v9, 0xffff0000, v97
	v_pk_add_f32 v[148:149], v[148:149], v[8:9]
	v_lshlrev_b32_e32 v8, 16, v98
	v_and_b32_e32 v9, 0xffff0000, v98
	v_pk_add_f32 v[150:151], v[150:151], v[8:9]
	v_lshlrev_b32_e32 v8, 16, v99
	v_and_b32_e32 v9, 0xffff0000, v99
	v_pk_add_f32 v[152:153], v[152:153], v[8:9]
	v_lshlrev_b32_e32 v8, 16, v100
	v_and_b32_e32 v9, 0xffff0000, v100
	v_pk_add_f32 v[134:135], v[134:135], v[8:9]
	v_lshlrev_b32_e32 v8, 16, v101
	v_and_b32_e32 v9, 0xffff0000, v101
	v_pk_add_f32 v[148:149], v[148:149], v[8:9]
	v_lshlrev_b32_e32 v8, 16, v102
	v_and_b32_e32 v9, 0xffff0000, v102
	v_pk_add_f32 v[150:151], v[150:151], v[8:9]
	v_lshlrev_b32_e32 v8, 16, v103
	v_and_b32_e32 v9, 0xffff0000, v103
	v_pk_add_f32 v[152:153], v[152:153], v[8:9]
	v_lshlrev_b32_e32 v8, 16, v104
	v_and_b32_e32 v9, 0xffff0000, v104
	v_pk_add_f32 v[134:135], v[134:135], v[8:9]
	v_lshlrev_b32_e32 v8, 16, v105
	v_and_b32_e32 v9, 0xffff0000, v105
	v_pk_add_f32 v[148:149], v[148:149], v[8:9]
	v_lshlrev_b32_e32 v8, 16, v106
	v_and_b32_e32 v9, 0xffff0000, v106
	v_pk_add_f32 v[150:151], v[150:151], v[8:9]
	v_lshlrev_b32_e32 v8, 16, v107
	v_and_b32_e32 v9, 0xffff0000, v107
	v_pk_add_f32 v[152:153], v[152:153], v[8:9]
	v_lshlrev_b32_e32 v8, 16, v108
	v_and_b32_e32 v9, 0xffff0000, v108
	v_pk_add_f32 v[134:135], v[134:135], v[8:9]
	v_lshlrev_b32_e32 v8, 16, v109
	v_and_b32_e32 v9, 0xffff0000, v109
	v_pk_add_f32 v[148:149], v[148:149], v[8:9]
	v_lshlrev_b32_e32 v8, 16, v110
	v_and_b32_e32 v9, 0xffff0000, v110
	v_pk_add_f32 v[150:151], v[150:151], v[8:9]
	v_lshlrev_b32_e32 v8, 16, v111
	v_and_b32_e32 v9, 0xffff0000, v111
	v_pk_add_f32 v[152:153], v[152:153], v[8:9]
	v_lshlrev_b32_e32 v8, 16, v112
	v_and_b32_e32 v9, 0xffff0000, v112
	v_pk_add_f32 v[134:135], v[134:135], v[8:9]
	v_lshlrev_b32_e32 v8, 16, v113
	v_and_b32_e32 v9, 0xffff0000, v113
	v_pk_add_f32 v[148:149], v[148:149], v[8:9]
	v_lshlrev_b32_e32 v8, 16, v114
	v_and_b32_e32 v9, 0xffff0000, v114
	v_pk_add_f32 v[150:151], v[150:151], v[8:9]
	v_lshlrev_b32_e32 v8, 16, v115
	v_and_b32_e32 v9, 0xffff0000, v115
	v_pk_add_f32 v[152:153], v[152:153], v[8:9]
	v_lshlrev_b32_e32 v8, 16, v116
	v_and_b32_e32 v9, 0xffff0000, v116
	v_pk_add_f32 v[134:135], v[134:135], v[8:9]
	v_lshlrev_b32_e32 v8, 16, v117
	v_and_b32_e32 v9, 0xffff0000, v117
	v_pk_add_f32 v[148:149], v[148:149], v[8:9]
	v_lshlrev_b32_e32 v8, 16, v118
	v_and_b32_e32 v9, 0xffff0000, v118
	v_pk_add_f32 v[150:151], v[150:151], v[8:9]
	v_lshlrev_b32_e32 v8, 16, v119
	v_and_b32_e32 v9, 0xffff0000, v119
	v_pk_add_f32 v[152:153], v[152:153], v[8:9]
	v_lshlrev_b32_e32 v8, 16, v120
	v_and_b32_e32 v9, 0xffff0000, v120
	v_pk_add_f32 v[134:135], v[134:135], v[8:9]
	v_lshlrev_b32_e32 v8, 16, v121
	v_and_b32_e32 v9, 0xffff0000, v121
	v_pk_add_f32 v[148:149], v[148:149], v[8:9]
	v_lshlrev_b32_e32 v8, 16, v122
	v_and_b32_e32 v9, 0xffff0000, v122
	v_pk_add_f32 v[150:151], v[150:151], v[8:9]
	v_lshlrev_b32_e32 v8, 16, v123
	v_and_b32_e32 v9, 0xffff0000, v123
	v_pk_add_f32 v[152:153], v[152:153], v[8:9]
